# SSD segment B: eight exec-masked decay blocks made branch-free with all LDS reads up front and one wait (on top of the counted-wait loop top)
# speedup vs baseline: 1.0042x; 1.0013x over previous
; #define BAR_LDS() asm volatile("s_waitcnt lgkmcnt(0)\n\ts_barrier" ::: "memory")
; template <bool DRY> __device__ __forceinline__ void ssd_unit(const Args& A, char* lds, int b, int h) {
;     ...
;         if (c + 1 < SEQL / 64) { const size_t o = (size_t)(c + 1) * 64 * 2048;
;             pre[0] = *(const bf16x8*)(pB + o); pre[1] = *(const bf16x8*)(pB + o + 32 * 2048); pre[2] = *(const bf16x8*)(pC + o); pre[3] = *(const bf16x8*)(pC + o + 32 * 2048); pre[4] = *(const bf16x8*)(pX + o); }
;         unsigned short zv[2][4];
; #pragma unroll
;         for (int pi = 0; pi < 2; ++pi)
; #pragma unroll
;             for (int r = 0; r < 4; ++r) zv[pi][r] = zn[pi][r];
;         if (c + 1 < SEQL / 64) {
; #pragma unroll
;             for (int pi = 0; pi < 2; ++pi)
; #pragma unroll
;                 for (int r = 0; r < 4; ++r) zn[pi][r] = pZ[((size_t)(c + 1) * 64 + r) * LD0 + 16 * pi]; }
;         BAR_LDS();
.LBB0_821:
	s_or_b64 exec, exec, s[66:67]
	v_lshl_add_u64 v[16:17], v[76:77], 0, s[56:57]
	v_add_co_u32_e32 v18, vcc, 0x80000, v16
	v_add_u32_e32 v137, v68, v133
	s_nop 0
	v_addc_co_u32_e32 v19, vcc, 0, v17, vcc
	v_add_co_u32_e32 v16, vcc, 0xa0000, v16
	v_add_u32_e32 v138, v68, v134
	s_nop 0
	v_addc_co_u32_e32 v17, vcc, 0, v17, vcc
	v_add_co_u32_e32 v36, vcc, 0x1ca0000, v44
	flat_load_dwordx4 v[20:23], v[18:19] offset:2048
	flat_load_dwordx4 v[28:31], v[18:19] offset:2560
	flat_load_dwordx4 v[24:27], v[16:17] offset:2048
	flat_load_dwordx4 v[32:35], v[16:17] offset:2560
	v_addc_co_u32_e32 v37, vcc, 0, v45, vcc
	v_add_co_u32_e32 v38, vcc, 0x1ca3000, v44
	v_lshl_add_u64 v[16:17], v[80:81], 0, s[58:59]
	s_nop 0
	v_addc_co_u32_e32 v39, vcc, 0, v45, vcc
	v_add_co_u32_e32 v40, vcc, 0x1ca6000, v44
	flat_load_dwordx4 v[16:19], v[16:17]
	s_nop 0
	v_addc_co_u32_e32 v41, vcc, 0, v45, vcc
	v_add_co_u32_e32 v42, vcc, 0x1ca9000, v44
	v_lshl_add_u32 v85, v56, 2, s4
	s_nop 0
	v_addc_co_u32_e32 v43, vcc, 0, v45, vcc
	flat_load_ushort v131, v[36:37]
	flat_load_ushort v145, v[38:39] offset:1024
	flat_load_ushort v146, v[40:41] offset:2048
	flat_load_ushort v129, v[42:43] offset:3072
	flat_load_ushort v67, v[42:43] offset:3104
	flat_load_ushort v147, v[40:41] offset:2080
	flat_load_ushort v148, v[38:39] offset:1056
	flat_load_ushort v130, v[36:37] offset:32
	s_waitcnt lgkmcnt(0)
	s_barrier
; __device__ __forceinline__ unsigned f2bf(float f) { return pk2(f, f) & 0xffffu; }
; template <bool DRY> __device__ __forceinline__ void ssd_unit(const Args& A, char* lds, int b, int h) {
;     ...
;         for (int ks = 0; ks < 4; ++ks) { const bf16x8 af = *(const bf16x8*)(CS + (lt * 16 + fr) * 136 + ks * 32 + 8 * fq);
; #pragma unroll
;             for (int si = 0; si < 2; ++si) { const bf16x8 bfv = *(const bf16x8*)(BS + ((st0 + si) * 16 + fr) * 136 + ks * 32 + 8 * fq); cb[si] = __builtin_amdgcn_mfma_f32_16x16x32_bf16(af, bfv, cb[si], 0, 0, 0); }
; #pragma unroll
;             for (int pi = 0; pi < 2; ++pi) { const bf16x8 sf = *(const bf16x8*)(SBF + ((pt0 + pi) * 16 + fr) * 136 + ks * 32 + 8 * fq); ya[pi] = __builtin_amdgcn_mfma_f32_16x16x32_bf16(af, sf, ya[pi], 0, 0, 0); } }
; #pragma unroll
;         for (int r = 0; r < 4; ++r) { const int l = lt * 16 + 4 * fq + r; const float al = DTA[64 + l];
; #pragma unroll
;             for (int si = 0; si < 2; ++si) { const int s = (st0 + si) * 16 + fr; const float v = (s <= l) ? cb[si][r] * __expf(al - DTA[64 + s]) : 0.f; GG[l * 72 + s] = (bf16)f2bf(v); }
;             const float ea = DTA[128 + l]; ya[0][r] *= ea; ya[1][r] *= ea; }
	ds_read_b128 v[36:39], v64
	ds_read_b128 v[40:43], v137 offset:17408
	v_add_u32_e32 v142, v125, v133
	v_add_u32_e32 v139, v125, v134
	ds_read_b128 v[44:47], v138 offset:17408
	ds_read_b128 v[88:91], v64 offset:192
	ds_read_b32 v82, v85 offset:256
	ds_read_b128 v[48:51], v142
	ds_read_b128 v[150:153], v137 offset:17600
	ds_read_b128 v[154:157], v139
	ds_read_b128 v[158:161], v138 offset:17600
	s_waitcnt lgkmcnt(0)
	v_mfma_f32_16x16x32_bf16 v[40:43], v[36:39], v[40:43], 0
	ds_read_b128 v[162:165], v64 offset:64
	ds_read_b128 v[166:169], v142 offset:192
	v_lshl_add_u32 v87, v65, 2, s4
	v_mov_b32_e32 v83, 0
	v_mfma_f32_16x16x32_bf16 v[44:47], v[36:39], v[44:47], 0
	v_mfma_f32_16x16x32_bf16 v[48:51], v[36:39], v[48:51], 0
	v_mfma_f32_16x16x32_bf16 v[36:39], v[36:39], v[154:157], 0
	ds_read_b128 v[154:157], v137 offset:17472
	ds_read_b128 v[170:173], v64 offset:128
	ds_read_b128 v[174:177], v137 offset:17536
	s_waitcnt lgkmcnt(0)
	v_mfma_f32_16x16x32_bf16 v[40:43], v[162:165], v[154:157], v[40:43]
	ds_read_b128 v[154:157], v138 offset:17472
	ds_read_b128 v[178:181], v138 offset:17536
	s_waitcnt lgkmcnt(0)
	v_mfma_f32_16x16x32_bf16 v[44:47], v[162:165], v[154:157], v[44:47]
	ds_read_b128 v[154:157], v142 offset:64
	ds_read_b128 v[182:185], v142 offset:128
	s_waitcnt lgkmcnt(0)
	v_mfma_f32_16x16x32_bf16 v[48:51], v[162:165], v[154:157], v[48:51]
	ds_read_b128 v[154:157], v139 offset:64
	ds_read_b128 v[186:189], v139 offset:128
	v_mfma_f32_16x16x32_bf16 v[40:43], v[170:173], v[174:177], v[40:43]
	s_waitcnt lgkmcnt(0)
	v_mfma_f32_16x16x32_bf16 v[36:39], v[162:165], v[154:157], v[36:39]
	v_mfma_f32_16x16x32_bf16 v[154:157], v[170:173], v[182:185], v[48:51]
	v_mfma_f32_16x16x32_bf16 v[48:51], v[88:91], v[150:153], v[40:43]
	ds_read_b128 v[150:153], v139 offset:192
	v_mfma_f32_16x16x32_bf16 v[44:47], v[170:173], v[178:181], v[44:47]
	v_mfma_f32_16x16x32_bf16 v[36:39], v[170:173], v[186:189], v[36:39]
	v_mfma_f32_16x16x32_bf16 v[44:47], v[88:91], v[158:161], v[44:47]
	v_mfma_f32_16x16x32_bf16 v[40:43], v[88:91], v[166:169], v[154:157]
	s_waitcnt lgkmcnt(0)
	v_mfma_f32_16x16x32_bf16 v[36:39], v[88:91], v[150:153], v[36:39]
	v_lshl_add_u32 v88, v99, 2, s4
	v_mov_b32_e32 v89, s4
	ds_read_b32 v190, v87 offset:256
	ds_read_b32 v191, v88 offset:256
	ds_read2_b32 v[192:193], v85 offset0:65 offset1:66
	ds_read2_b32 v[194:195], v85 offset0:67 offset1:128
	ds_read2_b32 v[196:197], v85 offset0:129 offset1:130
	ds_read_b32 v198, v85 offset:524
	ds_read_b32 v199, v89 offset:508
	s_waitcnt lgkmcnt(0)
	v_sub_f32_e32 v200, v82, v190
	v_sub_f32_e32 v201, v82, v191
	v_sub_f32_e32 v202, v192, v190
	v_sub_f32_e32 v203, v192, v191
	v_sub_f32_e32 v204, v193, v190
	v_sub_f32_e32 v205, v193, v191
	v_sub_f32_e32 v206, v194, v190
	v_sub_f32_e32 v207, v194, v191
	v_mul_f32_e32 v200, 0x3fb8aa3b, v200
	v_mul_f32_e32 v201, 0x3fb8aa3b, v201
	v_mul_f32_e32 v202, 0x3fb8aa3b, v202
	v_mul_f32_e32 v203, 0x3fb8aa3b, v203
	v_mul_f32_e32 v204, 0x3fb8aa3b, v204
	v_mul_f32_e32 v205, 0x3fb8aa3b, v205
	v_mul_f32_e32 v206, 0x3fb8aa3b, v206
	v_mul_f32_e32 v207, 0x3fb8aa3b, v207
	v_exp_f32_e32 v200, v200
	v_exp_f32_e32 v201, v201
	v_exp_f32_e32 v202, v202
	v_exp_f32_e32 v203, v203
	v_exp_f32_e32 v204, v204
	v_exp_f32_e32 v205, v205
	v_exp_f32_e32 v206, v206
	v_exp_f32_e32 v207, v207
	v_mul_f32_e32 v200, v48, v200
	v_mul_f32_e32 v201, v44, v201
	v_mul_f32_e32 v202, v49, v202
	v_mul_f32_e32 v203, v45, v203
	v_mul_f32_e32 v204, v50, v204
	v_mul_f32_e32 v205, v46, v205
	v_mul_f32_e32 v206, v51, v206
	v_mul_f32_e32 v207, v47, v207
	v_cndmask_b32_e64 v200, 0, v200, s[6:7]
	v_cndmask_b32_e64 v201, 0, v201, s[8:9]
	v_cndmask_b32_e64 v202, 0, v202, s[10:11]
	v_cndmask_b32_e64 v203, 0, v203, s[12:13]
	v_cndmask_b32_e64 v204, 0, v204, s[14:15]
	v_cndmask_b32_e64 v205, 0, v205, s[16:17]
	v_cndmask_b32_e64 v206, 0, v206, s[18:19]
	v_cndmask_b32_e64 v207, 0, v207, s[20:21]
	v_cvt_pk_bf16_f32 v200, v200, s0
	v_cvt_pk_bf16_f32 v201, v201, s0
	v_cvt_pk_bf16_f32 v202, v202, s0
	v_cvt_pk_bf16_f32 v203, v203, s0
	v_cvt_pk_bf16_f32 v204, v204, s0
	v_cvt_pk_bf16_f32 v205, v205, s0
	v_cvt_pk_bf16_f32 v206, v206, s0
	v_cvt_pk_bf16_f32 v207, v207, s0
	ds_write_b16 v108, v200
	ds_write_b16 v107, v201
	ds_write_b16 v112, v202
	ds_write_b16 v111, v203
	ds_write_b16 v115, v204
	ds_write_b16 v114, v205
	ds_write_b16 v116, v206
	ds_write_b16 v119, v207
	v_mov_b32_e32 v83, v195
	v_mov_b32_e32 v45, v196
	v_mov_b32_e32 v49, v197
	v_mov_b32_e32 v50, v198
	v_mov_b32_e32 v51, v199
	s_and_b64 s[98:99], exec, s[26:27]
	s_cbranch_scc1 .Lssd_dts_skip
	v_mul_f32_e64 v190, v69, -v100
	v_mov_b32_e32 v191, 0
	s_nop 1
	v_mov_b32_dpp v191, v190 row_shr:1 row_mask:0xf bank_mask:0xf
	v_fma_f32 v190, v69, -v100, v191
	v_cvt_f32_u32_e32 v192, v98
	s_nop 0
	v_add_f32_dpp v190, v190, v190 row_shr:2 row_mask:0xf bank_mask:0xf bound_ctrl:1
	v_min_f32_e32 v193, 1.0, v192
	v_add_f32_e32 v194, -1.0, v192
	v_add_f32_dpp v190, v190, v190 row_shr:4 row_mask:0xf bank_mask:0xf bound_ctrl:1
	v_add_f32_e32 v195, -2.0, v192
	v_med3_f32 v194, v194, 0, 1.0
	v_add_f32_dpp v190, v190, v190 row_shr:8 row_mask:0xf bank_mask:0xf bound_ctrl:1
	v_med3_f32 v195, v195, 0, 1.0
	s_nop 0
	v_readlane_b32 s98, v190, 15
	v_readlane_b32 s99, v190, 31
	v_readlane_b32 s100, v190, 47
	v_mul_f32_e32 v191, s98, v193
	v_fma_f32 v191, v194, s99, v191
	v_fma_f32 v191, v195, s100, v191
	v_add_f32_e32 v190, v190, v191
	v_mul_f32_e32 v191, 0x3fb8aa3b, v190
	v_readlane_b32 s98, v190, 63
	v_exp_f32_e32 v191, v191
	s_and_b32 s99, s0, 0x100
	v_sub_f32_e32 v192, s98, v190
	v_mul_f32_e32 v192, 0x3fb8aa3b, v192
	v_exp_f32_e32 v192, v192
	v_lshl_add_u32 v193, s99, 2, v126
	ds_write2st64_b32 v193, v69, v190 offset1:1
	ds_write2st64_b32 v193, v191, v192 offset0:2 offset1:3
	s_cmp_gt_u32 s1, 28
	s_cbranch_scc1 .Lssd_dts_skip
	global_load_dword v69, v[74:75], off
